# retention X-block LDS reads software-pipelined (counted lgkmcnt), bit-identical math
# baseline (speedup 1.0000x reference)
.LBB0_588:
	s_add_i32 s84, s84, s33
	s_add_i32 s92, s92, s33
	s_cmpk_lt_i32 s84, 0x100
	s_cbranch_scc0 .LBB0_616
	v_lshrrev_b32_e32 v156, 3, v0
	v_bfe_u32 v4, v0, 5, 1
	v_xor_b32_e32 v5, 63, v156
	v_cvt_f32_ubyte0_e32 v194, v5
	v_and_b32_e32 v6, 12, v0
	v_lshl_or_b32 v6, v4, 1, v6
	v_mov_b32_e32 v5, 0x11000
	v_mad_u32_u24 v196, v6, s93, 0
	v_mov_b32_e32 v7, 0x90
	v_mad_u32_u24 v197, v6, v7, v5
	v_bfe_u32 v6, v0, 2, 2
	v_lshl_or_b32 v6, v4, 3, v6
	v_mad_u32_u24 v200, v6, v7, v5
	v_lshrrev_b32_e32 v154, 4, v0
	v_lshlrev_b32_e32 v155, 2, v4
	v_lshrrev_b32_e32 v6, 2, v0
	v_and_b32_e32 v157, 8, v6
	v_and_b32_e32 v6, 31, v0
	v_or_b32_e32 v199, 32, v6
	v_lshlrev_b32_e32 v8, 1, v6
	v_lshl_or_b32 v166, v4, 14, v8
	v_lshlrev_b32_e32 v6, 2, v0
	v_and_b32_e32 v6, 12, v6
	v_and_or_b32 v201, v0, 16, v6
	v_add_u32_e32 v195, 0, v158
	v_lshlrev_b32_e32 v160, 10, v4
	v_or_b32_e32 v198, 8, v155
	v_or_b32_e32 v206, 9, v155
	v_or_b32_e32 v207, 10, v155
	v_or_b32_e32 v208, 11, v155
	v_or_b32_e32 v209, 16, v155
	v_or_b32_e32 v210, 17, v155
	v_or_b32_e32 v211, 18, v155
	v_or_b32_e32 v212, 19, v155
	v_or_b32_e32 v213, 24, v155
	v_or_b32_e32 v214, 25, v155
	v_or_b32_e32 v215, 26, v155
	v_or_b32_e32 v216, 27, v155
	v_mov_b32_e32 v161, v2
	v_mov_b32_e32 v163, v2
	v_mov_b32_e32 v165, v2
	v_mov_b32_e32 v167, v2
	v_add_u32_e32 v217, 0x15800, v158
	v_and_b32_e32 v6, 15, v0
	v_lshlrev_b32_e32 v6, 4, v6
	v_lshl_or_b32 v162, v154, 11, v6
	v_and_b32_e32 v6, 7, v0
	v_lshlrev_b32_e32 v6, 4, v6
	v_lshl_or_b32 v164, v156, 12, v6

.LBB0_593:
	v_lshl_add_u64 v[192:193], s[82:83], 0, v[178:179]
	s_mov_b32 s70, 0x7a00000
	v_add_co_u32_e32 v4, vcc, s70, v192
	s_mov_b32 s70, 0x7a10000
	s_nop 0
	v_addc_co_u32_e32 v5, vcc, 0, v193, vcc
	v_add_co_u32_e32 v6, vcc, s70, v192
	ds_write_b128 v223, v[114:117]
	ds_write_b128 v223, v[118:121] offset:8704
	ds_write_b128 v223, v[134:137] offset:17408
	ds_write_b128 v223, v[142:145] offset:26112
	v_addc_co_u32_e32 v7, vcc, 0, v193, vcc
	s_mov_b32 s70, 0x7a20000
	global_load_dwordx4 v[114:117], v[4:5], off offset:256
	global_load_dwordx4 v[118:121], v[6:7], off offset:256
	v_add_co_u32_e32 v4, vcc, s70, v192
	v_lshlrev_b32_e32 v8, 16, v124
	s_nop 0
	v_addc_co_u32_e32 v5, vcc, 0, v193, vcc
	v_add_co_u32_e32 v6, vcc, 0x7a30000, v192
	v_and_b32_e32 v9, 0xffff0000, v124
	s_nop 0
	v_addc_co_u32_e32 v7, vcc, 0, v193, vcc
	global_load_dwordx4 v[134:137], v[4:5], off offset:256
	global_load_dwordx4 v[142:145], v[6:7], off offset:256
	v_lshlrev_b32_e32 v4, 16, v122
	v_and_b32_e32 v5, 0xffff0000, v122
	v_lshlrev_b32_e32 v6, 16, v123
	v_and_b32_e32 v7, 0xffff0000, v123
	v_lshlrev_b32_e32 v10, 16, v125
	v_and_b32_e32 v11, 0xffff0000, v125
	v_pk_mul_f32 v[6:7], v[186:187], v[6:7]
	v_pk_mul_f32 v[4:5], v[172:173], v[4:5]
	v_pk_mul_f32 v[10:11], v[186:187], v[10:11]
	v_pk_mul_f32 v[8:9], v[172:173], v[8:9]
	v_cvt_pk_bf16_f32 v4, v4, v5
	v_cvt_pk_bf16_f32 v5, v6, v7
	v_cvt_pk_bf16_f32 v6, v8, v9
	v_cvt_pk_bf16_f32 v7, v10, v11
	ds_write_b128 v219, v[4:7]
	v_lshlrev_b32_e32 v4, 16, v126
	v_and_b32_e32 v5, 0xffff0000, v126
	v_lshlrev_b32_e32 v6, 16, v127
	v_and_b32_e32 v7, 0xffff0000, v127
	v_lshlrev_b32_e32 v8, 16, v128
	v_and_b32_e32 v9, 0xffff0000, v128
	v_lshlrev_b32_e32 v10, 16, v129
	v_and_b32_e32 v11, 0xffff0000, v129
	v_pk_mul_f32 v[6:7], v[188:189], v[6:7]
	v_pk_mul_f32 v[4:5], v[174:175], v[4:5]
	v_pk_mul_f32 v[10:11], v[188:189], v[10:11]
	v_pk_mul_f32 v[8:9], v[174:175], v[8:9]
	v_cvt_pk_bf16_f32 v4, v4, v5
	v_cvt_pk_bf16_f32 v5, v6, v7
	v_cvt_pk_bf16_f32 v6, v8, v9
	v_cvt_pk_bf16_f32 v7, v10, v11
	ds_write_b128 v219, v[4:7] offset:9216
	s_waitcnt lgkmcnt(0)
	s_barrier
	v_add_u32_e32 v251, v171, v158
	ds_read_b128 v[4:7], v245 offset:34816
	ds_read_b128 v[8:11], v251
	v_cndmask_b32_e64 v3, 0, 1, s[72:73]
	v_cmp_ne_u32_e64 s[70:71], 1, v3
	s_andn2_b64 vcc, exec, s[72:73]
	s_mov_b64 s[74:75], -1
	s_cbranch_vccnz .LBB0_595
	ds_read_b128 v[12:15], v245 offset:34848
	ds_read_b128 v[202:205], v251 offset:32
	ds_read_b128 v[154:157], v245 offset:34880
	ds_read_b128 v[160:163], v251 offset:64
	ds_read_b128 v[164:167], v245 offset:34912
	ds_read_b128 v[194:197], v251 offset:96
	s_mov_b64 s[74:75], 0
	s_waitcnt lgkmcnt(6)
	v_mfma_f32_32x32x16_bf16 v[82:97], v[4:7], v[8:11], 0
	ds_read_b128 v[4:7], v245 offset:34944
	ds_read_b128 v[8:11], v251 offset:128
	s_waitcnt lgkmcnt(6)
	v_mfma_f32_32x32x16_bf16 v[82:97], v[12:15], v[202:205], v[82:97]
	ds_read_b128 v[12:15], v245 offset:34976
	ds_read_b128 v[202:205], v251 offset:160
	s_waitcnt lgkmcnt(6)
	v_mfma_f32_32x32x16_bf16 v[82:97], v[154:157], v[160:163], v[82:97]
	ds_read_b128 v[154:157], v245 offset:35008
	ds_read_b128 v[160:163], v251 offset:192
	s_waitcnt lgkmcnt(6)
	v_mfma_f32_32x32x16_bf16 v[82:97], v[164:167], v[194:197], v[82:97]
	ds_read_b128 v[164:167], v245 offset:35040
	ds_read_b128 v[194:197], v251 offset:224
	s_waitcnt lgkmcnt(6)
	v_mfma_f32_32x32x16_bf16 v[82:97], v[4:7], v[8:11], v[82:97]
	s_waitcnt lgkmcnt(4)
	v_mfma_f32_32x32x16_bf16 v[82:97], v[12:15], v[202:205], v[82:97]
	s_waitcnt lgkmcnt(2)
	v_mfma_f32_32x32x16_bf16 v[82:97], v[154:157], v[160:163], v[82:97]
	s_waitcnt lgkmcnt(0)
	v_mfma_f32_32x32x16_bf16 v[82:97], v[164:167], v[194:197], v[82:97]
.LBB0_595:
	s_andn2_b64 vcc, exec, s[74:75]
	s_cbranch_vccnz .LBB0_597
	ds_read_b128 v[12:15], v251 offset:8704
	ds_read_b128 v[154:157], v245 offset:34848
	ds_read_b128 v[160:163], v251 offset:32
	ds_read_b128 v[164:167], v251 offset:8736
	ds_read_b128 v[194:197], v245 offset:34880
	ds_read_b128 v[198:201], v251 offset:64
	ds_read_b128 v[206:209], v251 offset:8768
	ds_read_b128 v[210:213], v245 offset:34912
	ds_read_b128 v[214:217], v251 offset:96
	ds_read_b128 v[202:205], v251 offset:8800
	s_waitcnt lgkmcnt(10)
	v_mfma_f32_32x32x16_bf16 v[82:97], v[4:7], v[8:11], 0
	s_waitcnt lgkmcnt(9)
	v_mfma_f32_32x32x16_bf16 v[66:81], v[4:7], v[12:15], 0
	ds_read_b128 v[4:7], v245 offset:34944
	ds_read_b128 v[8:11], v251 offset:128
	ds_read_b128 v[12:15], v251 offset:8832
	s_waitcnt lgkmcnt(10)
	v_mfma_f32_32x32x16_bf16 v[82:97], v[154:157], v[160:163], v[82:97]
	s_waitcnt lgkmcnt(9)
	v_mfma_f32_32x32x16_bf16 v[66:81], v[154:157], v[164:167], v[66:81]
	ds_read_b128 v[154:157], v245 offset:34976
	ds_read_b128 v[160:163], v251 offset:160
	ds_read_b128 v[164:167], v251 offset:8864
	s_waitcnt lgkmcnt(10)
	v_mfma_f32_32x32x16_bf16 v[82:97], v[194:197], v[198:201], v[82:97]
	s_waitcnt lgkmcnt(9)
	v_mfma_f32_32x32x16_bf16 v[66:81], v[194:197], v[206:209], v[66:81]
	ds_read_b128 v[194:197], v245 offset:35008
	ds_read_b128 v[198:201], v251 offset:192
	ds_read_b128 v[206:209], v251 offset:8896
	s_waitcnt lgkmcnt(10)
	v_mfma_f32_32x32x16_bf16 v[82:97], v[210:213], v[214:217], v[82:97]
	s_waitcnt lgkmcnt(9)
	v_mfma_f32_32x32x16_bf16 v[66:81], v[210:213], v[202:205], v[66:81]
	ds_read_b128 v[210:213], v245 offset:35040
	ds_read_b128 v[214:217], v251 offset:224
	ds_read_b128 v[202:205], v251 offset:8928
	s_waitcnt lgkmcnt(10)
	v_mfma_f32_32x32x16_bf16 v[82:97], v[4:7], v[8:11], v[82:97]
	s_waitcnt lgkmcnt(9)
	v_mfma_f32_32x32x16_bf16 v[66:81], v[4:7], v[12:15], v[66:81]
	s_waitcnt lgkmcnt(7)
	v_mfma_f32_32x32x16_bf16 v[82:97], v[154:157], v[160:163], v[82:97]
	s_waitcnt lgkmcnt(6)
	v_mfma_f32_32x32x16_bf16 v[66:81], v[154:157], v[164:167], v[66:81]
	s_waitcnt lgkmcnt(4)
	v_mfma_f32_32x32x16_bf16 v[82:97], v[194:197], v[198:201], v[82:97]
	s_waitcnt lgkmcnt(3)
	v_mfma_f32_32x32x16_bf16 v[66:81], v[194:197], v[206:209], v[66:81]
	s_waitcnt lgkmcnt(1)
	v_mfma_f32_32x32x16_bf16 v[82:97], v[210:213], v[214:217], v[82:97]
	s_waitcnt lgkmcnt(0)
	v_mfma_f32_32x32x16_bf16 v[66:81], v[210:213], v[202:205], v[66:81]
	s_branch .LBB0_598

.LBB0_600:
	s_waitcnt lgkmcnt(0)
	s_barrier
	ds_read_b128 v[4:7], v245 offset:34816
	ds_read_b128 v[8:11], v251
	s_and_b64 vcc, exec, s[70:71]
	s_mov_b64 s[70:71], -1
	s_cbranch_vccnz .LBB0_602
	ds_read_b128 v[12:15], v245 offset:34848
	ds_read_b128 v[202:205], v251 offset:32
	ds_read_b128 v[154:157], v245 offset:34880
	ds_read_b128 v[160:163], v251 offset:64
	ds_read_b128 v[164:167], v245 offset:34912
	ds_read_b128 v[194:197], v251 offset:96
	s_mov_b64 s[70:71], 0
	s_waitcnt lgkmcnt(6)
	v_mfma_f32_32x32x16_bf16 v[98:113], v[4:7], v[8:11], v[82:97]
	ds_read_b128 v[4:7], v245 offset:34944
	ds_read_b128 v[8:11], v251 offset:128
	s_waitcnt lgkmcnt(6)
	v_mfma_f32_32x32x16_bf16 v[98:113], v[12:15], v[202:205], v[98:113]
	ds_read_b128 v[12:15], v245 offset:34976
	ds_read_b128 v[202:205], v251 offset:160
	s_waitcnt lgkmcnt(6)
	v_mfma_f32_32x32x16_bf16 v[98:113], v[154:157], v[160:163], v[98:113]
	ds_read_b128 v[154:157], v245 offset:35008
	ds_read_b128 v[160:163], v251 offset:192
	s_waitcnt lgkmcnt(6)
	v_mfma_f32_32x32x16_bf16 v[98:113], v[164:167], v[194:197], v[98:113]
	ds_read_b128 v[164:167], v245 offset:35040
	ds_read_b128 v[194:197], v251 offset:224
	s_waitcnt lgkmcnt(6)
	v_mfma_f32_32x32x16_bf16 v[98:113], v[4:7], v[8:11], v[98:113]
	s_waitcnt lgkmcnt(4)
	v_mfma_f32_32x32x16_bf16 v[98:113], v[12:15], v[202:205], v[98:113]
	s_waitcnt lgkmcnt(2)
	v_mfma_f32_32x32x16_bf16 v[98:113], v[154:157], v[160:163], v[98:113]
	s_waitcnt lgkmcnt(0)
	v_mfma_f32_32x32x16_bf16 v[98:113], v[164:167], v[194:197], v[98:113]
.LBB0_602:
	s_andn2_b64 vcc, exec, s[70:71]
	s_cbranch_vccnz .LBB0_604
	ds_read_b128 v[12:15], v251 offset:8704
	ds_read_b128 v[154:157], v245 offset:34848
	ds_read_b128 v[160:163], v251 offset:32
	ds_read_b128 v[164:167], v251 offset:8736
	ds_read_b128 v[194:197], v245 offset:34880
	ds_read_b128 v[198:201], v251 offset:64
	ds_read_b128 v[206:209], v251 offset:8768
	ds_read_b128 v[210:213], v245 offset:34912
	ds_read_b128 v[214:217], v251 offset:96
	ds_read_b128 v[202:205], v251 offset:8800
	s_waitcnt lgkmcnt(10)
	v_mfma_f32_32x32x16_bf16 v[82:97], v[4:7], v[8:11], v[82:97]
	s_waitcnt lgkmcnt(9)
	v_mfma_f32_32x32x16_bf16 v[66:81], v[4:7], v[12:15], v[66:81]
	ds_read_b128 v[4:7], v245 offset:34944
	ds_read_b128 v[8:11], v251 offset:128
	ds_read_b128 v[12:15], v251 offset:8832
	s_waitcnt lgkmcnt(10)
	v_mfma_f32_32x32x16_bf16 v[82:97], v[154:157], v[160:163], v[82:97]
	s_waitcnt lgkmcnt(9)
	v_mfma_f32_32x32x16_bf16 v[66:81], v[154:157], v[164:167], v[66:81]
	ds_read_b128 v[154:157], v245 offset:34976
	ds_read_b128 v[160:163], v251 offset:160
	ds_read_b128 v[164:167], v251 offset:8864
	s_waitcnt lgkmcnt(10)
	v_mfma_f32_32x32x16_bf16 v[82:97], v[194:197], v[198:201], v[82:97]
	s_waitcnt lgkmcnt(9)
	v_mfma_f32_32x32x16_bf16 v[66:81], v[194:197], v[206:209], v[66:81]
	ds_read_b128 v[194:197], v245 offset:35008
	ds_read_b128 v[198:201], v251 offset:192
	ds_read_b128 v[206:209], v251 offset:8896
	s_waitcnt lgkmcnt(10)
	v_mfma_f32_32x32x16_bf16 v[82:97], v[210:213], v[214:217], v[82:97]
	s_waitcnt lgkmcnt(9)
	v_mfma_f32_32x32x16_bf16 v[66:81], v[210:213], v[202:205], v[66:81]
	ds_read_b128 v[210:213], v245 offset:35040
	ds_read_b128 v[214:217], v251 offset:224
	ds_read_b128 v[202:205], v251 offset:8928
	s_waitcnt lgkmcnt(10)
	v_mfma_f32_32x32x16_bf16 v[82:97], v[4:7], v[8:11], v[82:97]
	s_waitcnt lgkmcnt(9)
	v_mfma_f32_32x32x16_bf16 v[66:81], v[4:7], v[12:15], v[66:81]
	s_waitcnt lgkmcnt(7)
	v_mfma_f32_32x32x16_bf16 v[82:97], v[154:157], v[160:163], v[82:97]
	s_waitcnt lgkmcnt(6)
	v_mfma_f32_32x32x16_bf16 v[66:81], v[154:157], v[164:167], v[66:81]
	s_waitcnt lgkmcnt(4)
	v_mfma_f32_32x32x16_bf16 v[82:97], v[194:197], v[198:201], v[82:97]
	s_waitcnt lgkmcnt(3)
	v_mfma_f32_32x32x16_bf16 v[66:81], v[194:197], v[206:209], v[66:81]
	s_waitcnt lgkmcnt(1)
	v_mfma_f32_32x32x16_bf16 v[82:97], v[210:213], v[214:217], v[82:97]
	s_waitcnt lgkmcnt(0)
	v_mfma_f32_32x32x16_bf16 v[66:81], v[210:213], v[202:205], v[66:81]
	s_nop 9
	v_mov_b64_e32 v[112:113], v[96:97]
	v_mov_b64_e32 v[110:111], v[94:95]
	v_mov_b64_e32 v[108:109], v[92:93]
	v_mov_b64_e32 v[106:107], v[90:91]
	v_mov_b64_e32 v[104:105], v[88:89]
	v_mov_b64_e32 v[102:103], v[86:87]
	v_mov_b64_e32 v[100:101], v[84:85]
	v_mov_b64_e32 v[98:99], v[82:83]
